# phase reorder: attention items run after the carry fix-up P4 (P4 reads LRU outputs while still cached); same barriers
# baseline (speedup 1.0000x reference)
; __device__ __forceinline__ unsigned xb_ld(unsigned* p)              { return __hip_atomic_load(p, __ATOMIC_RELAXED, __HIP_MEMORY_SCOPE_AGENT); }
; __device__ __forceinline__ unsigned xb_add(unsigned* p, unsigned v) { return __hip_atomic_fetch_add(p, v, __ATOMIC_RELAXED, __HIP_MEMORY_SCOPE_AGENT); }
; __device__ __forceinline__ void xcd_barrier_complete(unsigned* bar, unsigned x, unsigned& nloc, unsigned& nx) {
;     const unsigned G = gridDim.x * gridDim.y * gridDim.z;
;     unsigned sum, cnt, mine, sp = 0u;
;     for (;;) {
;         sum = 0u; cnt = 0u; mine = 0u;
; #pragma unroll
;         for (unsigned j = 0; j < 16; ++j) { const unsigned c = xb_ld(&bar[XB_XCNT(j)]); sum += c; cnt += (c > 0u) ? 1u : 0u; mine = (j == x) ? c : mine; }
;         if (sum == G) break;
;         __builtin_amdgcn_s_sleep(1);
;         if ((++sp & 255u) == 0u) { if (xb_ld(&bar[XB_TMO])) break; if (sp > XB_SPIN_CAP) { atomicAdd(&bar[XB_TMO], 1u); break; } }
;     }
;     nloc = mine > 0u ? mine : 1u; nx = cnt > 0u ? cnt : 1u;
; }
; __device__ __forceinline__ void xcd_barrier(const XcdBarrier& b) {
;     asm volatile("s_waitcnt vmcnt(0)" ::: "memory");
;     __syncthreads();
;     if (threadIdx.x == 0) {
;         unsigned* bar = b.bar;
;         __builtin_amdgcn_s_waitcnt(0);
;         unsigned nloc = b.st[0], nx = b.st[1];
;         if (nloc == 0u) { xcd_barrier_complete(bar, b.x, nloc, nx); b.st[0] = nloc; b.st[1] = nx; }
;         const unsigned old = xb_add(&bar[XB_XSUB(b.x)], 1u);
;         const unsigned gen = old / nloc;
;         if (old + 1u == (gen + 1u) * nloc) {
;             __builtin_amdgcn_fence(__ATOMIC_RELEASE, "agent");
;             asm volatile("s_waitcnt vmcnt(0)" ::: "memory");
;             const unsigned og = xb_add(&bar[XB_TOP], 1u);
;             const unsigned tg = og / nx;
;             if (og + 1u == (tg + 1u) * nx) xb_add(&bar[XB_TOPGEN], 1u);
;             else XB_SPIN(xb_ld(&bar[XB_TOPGEN]) == tg, bar);
;             __builtin_amdgcn_fence(__ATOMIC_ACQUIRE, "agent");
;             xb_add(&bar[XB_XGEN(b.x)], 1u);
;             asm volatile("s_waitcnt vmcnt(0)" ::: "memory");
;         } else {
;             XB_SPIN(xb_ld(&bar[XB_XGEN(b.x)]) == gen, bar);
;             __builtin_amdgcn_fence(__ATOMIC_ACQUIRE, "agent");
;             asm volatile("s_waitcnt vmcnt(0)" ::: "memory");
;         }
;     }
;     __syncthreads();
; }
.LBB0_234:
.LBB0_266:
	s_load_dwordx2 s[8:9], s[0:1], 0xc8
	s_waitcnt lgkmcnt(0)
	s_cmp_lt_i32 s8, 3
	s_cselect_b64 s[4:5], -1, 0
	s_cmp_gt_i32 s9, 3
	s_cselect_b64 s[6:7], -1, 0
	s_and_b64 s[4:5], s[4:5], s[6:7]
	s_andn2_b64 vcc, exec, s[4:5]
	s_cbranch_vccnz .LBB0_316
	s_waitcnt vmcnt(0)
	v_cmp_eq_u32_e32 vcc, 0, v202
	s_waitcnt vmcnt(0)
	s_barrier
	s_and_saveexec_b64 s[4:5], vcc
	s_cbranch_execz .LBB0_315
	s_add_i32 s6, 0, 0x21800
	v_mov_b32_e32 v0, s6
	s_waitcnt vmcnt(0) expcnt(0) lgkmcnt(0)
	ds_read_b32 v2, v0
	s_add_i32 s6, 0, 0x21804
	v_mov_b32_e32 v0, s6
	ds_read_b32 v0, v0
	s_waitcnt lgkmcnt(1)
	v_cmp_ne_u32_e32 vcc, 0, v2
	s_cbranch_vccnz .LBB0_283
	s_add_u32 s6, s26, 0x1c400200
	s_addc_u32 s7, s27, 0
	s_add_u32 s8, s26, 0x1c400400
	s_addc_u32 s9, s27, 0
	s_add_u32 s10, s26, 0x1c400500
	s_addc_u32 s11, s27, 0
	s_add_u32 s12, s26, 0x1c400600
	s_addc_u32 s13, s27, 0
	s_add_u32 s14, s26, 0x1c400700
	s_addc_u32 s15, s27, 0
	s_add_u32 s16, s26, 0x1c400800
	s_addc_u32 s17, s27, 0
	s_add_u32 s18, s26, 0x1c400900
	s_addc_u32 s19, s27, 0
	s_add_u32 s20, s26, 0x1c400a00
	s_addc_u32 s21, s27, 0
	s_add_u32 s22, s26, 0x1c400b00
	s_addc_u32 s23, s27, 0
	s_add_u32 s30, s26, 0x1c400c00
	s_addc_u32 s31, s27, 0
	s_add_u32 s34, s26, 0x1c400d00
	s_addc_u32 s35, s27, 0
	s_add_u32 s36, s26, 0x1c400e00
	s_addc_u32 s37, s27, 0
	s_add_u32 s38, s26, 0x1c400f00
	s_addc_u32 s39, s27, 0
	s_add_u32 s40, s26, 0x1c401000
	s_addc_u32 s41, s27, 0
	s_add_u32 s42, s26, 0x1c401100
	s_addc_u32 s43, s27, 0
	s_add_u32 s44, s26, 0x1c401200
	s_addc_u32 s45, s27, 0
	s_mul_i32 s54, s25, s33
	s_add_u32 s46, s26, 0x1c401300
	s_mul_i32 s54, s54, s24
	s_addc_u32 s47, s27, 0
	s_mov_b32 s55, 1
	v_mov_b32_e32 v16, 0
	s_branch .LBB0_271

; DI void phase_att(const Params& p, unsigned char* shm) {
;     const int wid = __builtin_amdgcn_readfirstlane(threadIdx.x >> 6);
;     const bf16_t* Z = (const bf16_t*)(p.ws + WS_ZQKV); const bf16_t* GA = (const bf16_t*)(p.ws + WS_ZGA); bf16_t* YB = (bf16_t*)(p.ws + WS_YB);
;     for (int it = blockIdx.x; it < 1024; it += gridDim.x) {
;         const int hp = it & 1, g = (it >> 1) & 3, n = it >> 3;
;         const int head = g * 4 + hp * 2 + (wid >> 2), qw = 32 * (wid & 3);
;         const int kfirst = n == 0 ? 0 : (n - 1) * 128, NT = (n == 0 || n == 127) ? 4 : 6, kt0 = kfirst - n * 128;
;         __syncthreads();
;         const size_t go = (size_t)(n * 128 + qw) * 2048 + head * 128;
;         att::attn_item(Z + (size_t)(n * 128 + qw) * 3072 + head * 128, Z + (size_t)kfirst * 3072 + 2048 + g * 128, Z + (size_t)kfirst * 3072 + 2560 + g * 128,
;                        GA + go, YB + go, NT, kt0, qw, p.in[10][head], (char*)shm);
;     }
;     __syncthreads();
; }
; DI void phase_mixers(const Params& p, unsigned char* shm) { if (p.mix_mask & 1) phase_lru(p, shm); if (p.mix_mask & 2) phase_att(p, shm); }
.LBB0_381:
	s_or_b64 exec, exec, s[8:9]
	s_load_dword s4, s[0:1], 0xd0
	s_waitcnt lgkmcnt(0)
	s_bitcmp0_b32 s4, 1
	s_cbranch_scc1 .Latt_done
	s_cmpk_gt_i32 s2, 0x3ff
	v_readfirstlane_b32 s6, v202
	s_cbranch_scc1 .LBB0_265
	v_lshrrev_b32_e32 v180, 4, v202
	s_load_dwordx2 s[4:5], s[0:1], 0x80
	s_load_dwordx2 s[8:9], s[0:1], 0x50
	s_waitcnt vmcnt(0)
	v_add_u32_e32 v10, 32, v180
	v_and_b32_e32 v5, 48, v180
	v_lshrrev_b32_e32 v6, 3, v202
	v_and_b32_e32 v11, 0x70, v10
	v_lshlrev_b32_e32 v12, 1, v10
	v_lshlrev_b32_e32 v3, 3, v202
	v_and_or_b32 v5, v6, 8, v5
	v_and_or_b32 v11, v12, 8, v11
	v_and_b32_e32 v4, 0x78, v3
	v_lshrrev_b32_e32 v5, 1, v5
	v_bfe_u32 v6, v3, 5, 2
	v_bfe_u32 v7, v202, 4, 2
	v_lshrrev_b32_e32 v11, 1, v11
	s_waitcnt lgkmcnt(0)
	s_add_u32 s11, s4, 0x8000000
	v_or_b32_e32 v5, v5, v6
	v_and_or_b32 v7, v203, 4, v7
	v_lshlrev_b32_e32 v8, 1, v4
	v_or_b32_e32 v6, v11, v6
	s_addc_u32 s22, s5, 0
	v_lshlrev_b32_e32 v5, 9, v5
	v_lshlrev_b32_e32 v7, 6, v7
	v_and_b32_e32 v9, 48, v8
	v_lshlrev_b32_e32 v6, 9, v6
	s_add_u32 s23, s4, 0xe000000
	v_or3_b32 v5, v5, v7, v9
	v_or3_b32 v7, v6, v7, v9
	v_lshlrev_b32_e32 v9, 4, v202
	v_lshlrev_b32_e32 v11, 1, v202
	s_addc_u32 s30, s5, 0
	s_lshr_b32 s31, s6, 8
	s_lshr_b32 s6, s6, 1
	v_bfe_u32 v0, v202, 5, 1
	v_and_b32_e32 v6, 0xc0, v9
	v_and_b32_e32 v11, 32, v11
	v_and_b32_e32 v3, 0x118, v3
	v_and_b32_e32 v188, 31, v202
	s_and_b32 s34, s6, 0x60
	v_or3_b32 v3, v11, v6, v3
	v_lshlrev_b32_e32 v11, 8, v180
	v_and_b32_e32 v12, 0x70, v202
	v_lshlrev_b32_e32 v10, 8, v10
	v_lshlrev_b32_e32 v191, 4, v0
	s_cmp_lg_u32 0, -1
	v_bitop3_b32 v11, v8, v11, v12 bitop3:0xde
	v_bitop3_b32 v13, v8, v10, v12 bitop3:0xde
	v_lshlrev_b32_e32 v8, 8, v188
	v_and_b32_e32 v9, 0x70, v9
	v_or_b32_e32 v10, 32, v191
	s_cselect_b32 s10, 0, 0
	v_bitop3_b32 v18, v10, v8, v9 bitop3:0xde
	v_or_b32_e32 v10, 64, v191
	v_add_u32_e32 v190, s10, v3
	v_bitop3_b32 v19, v10, v8, v9 bitop3:0xde
	v_or_b32_e32 v10, 0x60, v191
	v_lshlrev_b32_e32 v193, 2, v0
	s_addk_i32 s10, 0x4000
	v_lshlrev_b32_e32 v2, 3, v0
	v_bitop3_b32 v20, v10, v8, v9 bitop3:0xde
	v_or_b32_e32 v10, 0x80, v191
	v_add_u32_e32 v194, s10, v3
	v_mul_u32_u24_e32 v196, 0x440, v0
	v_or_b32_e32 v0, 1, v193
	s_movk_i32 s39, 0x110
	v_mov_b32_e32 v3, 0x990
	v_bitop3_b32 v21, v10, v8, v9 bitop3:0xde
	v_or_b32_e32 v10, 0xa0, v191
	v_mul_u32_u24_e32 v197, 0x110, v0
	v_mad_u32_u24 v198, v0, s39, v3
	v_sub_u32_e32 v0, v193, v188
	v_mul_u32_u24_e32 v6, 0xc00, v180
	v_bitop3_b32 v22, v10, v8, v9 bitop3:0xde
	v_or_b32_e32 v10, 0xc0, v191
	v_subrev_u32_e32 v199, s34, v0
	v_and_b32_e32 v0, 15, v202
	v_mov_b32_e32 v1, 0
	v_or_b32_e32 v4, v6, v4
	v_bitop3_b32 v23, v10, v8, v9 bitop3:0xde
	v_or_b32_e32 v10, 0xe0, v191
	v_lshlrev_b32_e32 v0, 4, v0
	v_and_b32_e32 v189, 63, v202
	v_add_u32_e32 v6, 0x18000, v4
	v_bitop3_b32 v15, v191, v8, v9 bitop3:0xde
	v_bitop3_b32 v9, v10, v8, v9 bitop3:0xde
	v_or_b32_e32 v192, s34, v188
	v_add_u32_e32 v8, 0x30000, v4
	v_add_u32_e32 v10, 0x48000, v4
	v_add_u32_e32 v12, 0x78000, v4
	v_add_u32_e32 v14, 0x60000, v4
	v_lshl_add_u64 v[16:17], s[4:5], 0, v[0:1]
	s_mov_b64 s[4:5], 0x81b1400
	s_movk_i32 s35, 0x1800
	v_mul_u32_u24_e32 v178, 0x1800, v188
	v_mov_b32_e32 v179, v1
	s_mov_b32 s36, 0x18000
	s_or_b32 s37, s6, 0xffffff9f
	v_cmp_gt_u32_e64 s[6:7], 32, v189
	s_movk_i32 s38, 0x4000
	v_sub_u32_e32 v195, v193, v192
	s_sub_i32 s40, 0, s34
	v_lshl_add_u64 v[182:183], v[16:17], 0, s[4:5]
	v_mov_b32_e32 v181, v1
	v_lshlrev_b32_e32 v184, 1, v2
	v_lshlrev_b32_e32 v200, 1, v4
	v_lshlrev_b32_e32 v201, 1, v6
	s_movk_i32 s41, 0x101
	s_mov_b32 s42, 0x10000
	s_mov_b32 s43, 0x413504f3
	s_mov_b32 s44, 0x42b504f3
	s_mov_b32 s10, 0x3e0293ee
	v_lshlrev_b32_e32 v204, 1, v8
	v_lshlrev_b32_e32 v205, 1, v10
	v_lshlrev_b32_e32 v206, 1, v12
	v_lshlrev_b32_e32 v207, 1, v14
	s_mov_b32 s45, 0xfff70000
	s_mov_b32 s46, 0xfffa0000
	s_mov_b64 s[12:13], 0xc0000
	s_mov_b32 s47, 0x8000
	s_mov_b32 s48, 0xc000
	s_mov_b32 s49, 0x14000
	s_mov_b32 s50, 0x1c000
	v_mov_b32_e32 v185, v1
	v_add_u32_e32 v208, 0, v5
	v_add_u32_e32 v209, 0, v7
	v_add_u32_e32 v210, 0, v11
	v_add_u32_e32 v211, 0, v13
	v_add_u32_e32 v212, 0, v15
	v_add_u32_e32 v213, 0, v18
	v_add_u32_e32 v214, 0, v19
	v_add_u32_e32 v215, 0, v20
	v_add_u32_e32 v216, 0, v21
	v_add_u32_e32 v217, 0, v22
	v_add_u32_e32 v218, 0, v23
	v_add_u32_e32 v219, 0, v9
	v_mov_b32_e32 v220, 0xf149f2ca
	s_mov_b32 s51, s2
	s_branch .LBB0_238

; __device__ __forceinline__ unsigned xb_ld(unsigned* p)              { return __hip_atomic_load(p, __ATOMIC_RELAXED, __HIP_MEMORY_SCOPE_AGENT); }
; __device__ __forceinline__ unsigned xb_add(unsigned* p, unsigned v) { return __hip_atomic_fetch_add(p, v, __ATOMIC_RELAXED, __HIP_MEMORY_SCOPE_AGENT); }
; #define XB_SPIN(cond, bar) do { unsigned _sp = 0; while (cond) { __builtin_amdgcn_s_sleep(1); \
;     if ((++_sp & 255u) == 0u) { if (xb_ld(&(bar)[XB_TMO])) break; if (_sp > XB_SPIN_CAP) { atomicAdd(&(bar)[XB_TMO], 1u); break; } } } } while (0)
; __device__ __forceinline__ void xcd_barrier(const XcdBarrier& b) {
;     asm volatile("s_waitcnt vmcnt(0)" ::: "memory");
;     __syncthreads();
;     if (threadIdx.x == 0) {
;         unsigned* bar = b.bar;
;         __builtin_amdgcn_s_waitcnt(0);
;         unsigned nloc = b.st[0], nx = b.st[1];
;         if (nloc == 0u) { xcd_barrier_complete(bar, b.x, nloc, nx); b.st[0] = nloc; b.st[1] = nx; }
;         const unsigned old = xb_add(&bar[XB_XSUB(b.x)], 1u);
;         const unsigned gen = old / nloc;
;         if (old + 1u == (gen + 1u) * nloc) {
;             __builtin_amdgcn_fence(__ATOMIC_RELEASE, "agent");
;             asm volatile("s_waitcnt vmcnt(0)" ::: "memory");
;             const unsigned og = xb_add(&bar[XB_TOP], 1u);
;             const unsigned tg = og / nx;
;             if (og + 1u == (tg + 1u) * nx) xb_add(&bar[XB_TOPGEN], 1u);
;             else XB_SPIN(xb_ld(&bar[XB_TOPGEN]) == tg, bar);
;             __builtin_amdgcn_fence(__ATOMIC_ACQUIRE, "agent");
;             xb_add(&bar[XB_XGEN(b.x)], 1u);
;             asm volatile("s_waitcnt vmcnt(0)" ::: "memory");
;         } else {
;             XB_SPIN(xb_ld(&bar[XB_XGEN(b.x)]) == gen, bar);
;             __builtin_amdgcn_fence(__ATOMIC_ACQUIRE, "agent");
;             asm volatile("s_waitcnt vmcnt(0)" ::: "memory");
;         }
;     }
;     __syncthreads();
; }
.Latt_done:
	s_load_dwordx2 s[4:5], s[0:1], 0xc8
	s_waitcnt lgkmcnt(0)
	v_mov_b64_e32 v[0:1], s[4:5]
	v_cmp_gt_i32_e32 vcc, 5, v0
	v_cmp_lt_i32_e64 s[4:5], 5, v1
	s_and_b64 s[6:7], vcc, s[4:5]
	s_and_saveexec_b64 s[4:5], s[6:7]
	s_cbranch_execz .LBB0_431
	s_waitcnt vmcnt(0)
	v_cmp_eq_u32_e32 vcc, 0, v202
	s_barrier
	s_and_saveexec_b64 s[6:7], vcc
	s_cbranch_execz .LBB0_430
	s_add_i32 s8, 0, 0x21800
	v_mov_b32_e32 v0, s8
	s_waitcnt vmcnt(0) expcnt(0) lgkmcnt(0)
	ds_read_b32 v2, v0
	s_add_i32 s8, 0, 0x21804
	v_mov_b32_e32 v0, s8
	ds_read_b32 v0, v0
	s_waitcnt lgkmcnt(1)
	v_cmp_ne_u32_e32 vcc, 0, v2
	s_cbranch_vccnz .LBB0_398
	s_add_u32 s8, s26, 0x1c400200
	s_addc_u32 s9, s27, 0
	s_add_u32 s10, s26, 0x1c400400
	s_addc_u32 s11, s27, 0
	s_add_u32 s12, s26, 0x1c400500
	s_addc_u32 s13, s27, 0
	s_add_u32 s14, s26, 0x1c400600
	s_addc_u32 s15, s27, 0
	s_add_u32 s16, s26, 0x1c400700
	s_addc_u32 s17, s27, 0
	s_add_u32 s18, s26, 0x1c400800
	s_addc_u32 s19, s27, 0
	s_add_u32 s20, s26, 0x1c400900
	s_addc_u32 s21, s27, 0
	s_add_u32 s22, s26, 0x1c400a00
	s_addc_u32 s23, s27, 0
	s_add_u32 s30, s26, 0x1c400b00
	s_addc_u32 s31, s27, 0
	s_add_u32 s34, s26, 0x1c400c00
	s_addc_u32 s35, s27, 0
	s_add_u32 s36, s26, 0x1c400d00
	s_addc_u32 s37, s27, 0
	s_add_u32 s38, s26, 0x1c400e00
	s_addc_u32 s39, s27, 0
	s_add_u32 s40, s26, 0x1c400f00
	s_addc_u32 s41, s27, 0
	s_add_u32 s42, s26, 0x1c401000
	s_addc_u32 s43, s27, 0
	s_add_u32 s44, s26, 0x1c401100
	s_addc_u32 s45, s27, 0
	s_add_u32 s46, s26, 0x1c401200
	s_addc_u32 s47, s27, 0
	s_mul_i32 s56, s25, s33
	s_add_u32 s48, s26, 0x1c401300
	s_mul_i32 s56, s56, s24
	s_addc_u32 s49, s27, 0
	s_mov_b32 s57, 1
	v_mov_b32_e32 v16, 0
	s_branch .LBB0_386
